# v28 + attention: per-pair K/V LDS-DMA issue deferred from the post-barrier loop head into each wave's first-tile softmax section
# baseline (speedup 1.0000x reference)
.LBB0_917:
	s_mov_b32 s100, 0
	s_cmp_lt_u32 s94, 3
	s_cselect_b64 s[78:79], -1, 0
	s_and_b64 vcc, exec, s[78:79]
	s_cbranch_vccnz .LBB0_920
	v_subrev_u32_e32 v246, s74, v148
	v_subrev_u32_e32 v247, s76, v150
	s_add_i32 s3, s2, 0xc0
	s_cmp_gt_i32 s3, s90
	s_cbranch_scc1 .Ldn_917
	s_mov_b32 s100, 1
	s_branch .LBB0_921
.Ldn_917:
	s_add_i32 s101, s2, 64
	s_lshl_b32 s101, s101, 8
	s_add_u32 s98, s74, s101
	s_addc_u32 s99, s75, 0
	s_add_i32 s101, s33, 0x4000
	s_and_b32 s101, s101, 0xc000
	s_add_i32 m0, s1, s101
	s_add_i32 s101, s101, s8
	global_load_lds_dwordx4 v246, s[98:99]
	s_add_i32 m0, m0, 0x2000
	s_add_u32 s98, s98, 0x2000
	s_addc_u32 s99, s99, 0
	global_load_lds_dwordx4 v246, s[98:99]
	s_mov_b32 m0, s101
	s_add_i32 s101, s2, 64
	s_lshl_b32 s101, s101, 8
	s_add_u32 s98, s76, s101
	s_addc_u32 s99, s77, 0
	global_load_lds_dwordx4 v247, s[98:99]
	s_add_i32 m0, m0, 0x2000
	s_add_u32 s98, s98, 0x2000
	s_addc_u32 s99, s99, 0
	global_load_lds_dwordx4 v247, s[98:99]
	s_lshl_b32 s101, s2, 8
	s_add_u32 s98, s74, s101
	s_addc_u32 s99, s75, 0
	s_and_b32 s101, s33, 0xc000
	s_add_i32 m0, s1, s101
	s_add_i32 s101, s101, s8
	global_load_lds_dwordx4 v246, s[98:99]
	s_add_i32 m0, m0, 0x2000
	s_add_u32 s98, s98, 0x2000
	s_addc_u32 s99, s99, 0
	global_load_lds_dwordx4 v246, s[98:99]
	s_mov_b32 m0, s101
	s_lshl_b32 s101, s2, 8
	s_add_u32 s98, s76, s101
	s_addc_u32 s99, s77, 0
	global_load_lds_dwordx4 v247, s[98:99]
	s_add_i32 m0, m0, 0x2000
	s_add_u32 s98, s98, 0x2000
	s_addc_u32 s99, s99, 0
	global_load_lds_dwordx4 v247, s[98:99]

.LBB0_924:
	s_cmp_eq_u32 s100, 0
	s_cbranch_scc1 .Lnd_917
	s_add_i32 s101, s2, 64
	s_lshl_b32 s101, s101, 8
	s_add_u32 s98, s74, s101
	s_addc_u32 s99, s75, 0
	s_add_i32 s101, s33, 0x4000
	s_and_b32 s101, s101, 0xc000
	s_add_i32 m0, s1, s101
	s_add_i32 s101, s101, s8
	global_load_lds_dwordx4 v246, s[98:99]
	s_add_i32 m0, m0, 0x2000
	s_add_u32 s98, s98, 0x2000
	s_addc_u32 s99, s99, 0
	global_load_lds_dwordx4 v246, s[98:99]
	s_mov_b32 m0, s101
	s_add_i32 s101, s2, 64
	s_lshl_b32 s101, s101, 8
	s_add_u32 s98, s76, s101
	s_addc_u32 s99, s77, 0
	global_load_lds_dwordx4 v247, s[98:99]
	s_add_i32 m0, m0, 0x2000
	s_add_u32 s98, s98, 0x2000
	s_addc_u32 s99, s99, 0
	global_load_lds_dwordx4 v247, s[98:99]
	s_lshl_b32 s101, s2, 8
	s_add_u32 s98, s74, s101
	s_addc_u32 s99, s75, 0
	s_and_b32 s101, s33, 0xc000
	s_add_i32 m0, s1, s101
	s_add_i32 s101, s101, s8
	global_load_lds_dwordx4 v246, s[98:99]
	s_add_i32 m0, m0, 0x2000
	s_add_u32 s98, s98, 0x2000
	s_addc_u32 s99, s99, 0
	global_load_lds_dwordx4 v246, s[98:99]
	s_mov_b32 m0, s101
	s_lshl_b32 s101, s2, 8
	s_add_u32 s98, s76, s101
	s_addc_u32 s99, s77, 0
	global_load_lds_dwordx4 v247, s[98:99]
	s_add_i32 m0, m0, 0x2000
	s_add_u32 s98, s98, 0x2000
	s_addc_u32 s99, s99, 0
	global_load_lds_dwordx4 v247, s[98:99]
	s_mov_b32 s100, 0

.LBB0_943:
	s_mov_b32 s100, 0
	s_cmp_lt_u32 s92, 3
	s_cselect_b64 s[6:7], -1, 0
	s_and_b64 vcc, exec, s[6:7]
	s_cbranch_vccnz .LBB0_946
	v_subrev_u32_e32 v246, s74, v150
	v_subrev_u32_e32 v247, s76, v152
	s_add_i32 s3, s2, 0xc0
	s_cmp_gt_i32 s3, s80
	s_cbranch_scc1 .Ldn_943
	s_mov_b32 s100, 1
	s_branch .LBB0_947
.Ldn_943:
	s_add_i32 s101, s2, 64
	s_lshl_b32 s101, s101, 8
	s_add_u32 s98, s74, s101
	s_addc_u32 s99, s75, 0
	s_add_i32 s101, s0, 0x4000
	s_and_b32 s101, s101, 0xc000
	s_add_i32 m0, s1, s101
	s_add_i32 s101, s101, s8
	global_load_lds_dwordx4 v246, s[98:99]
	s_add_i32 m0, m0, 0x2000
	s_add_u32 s98, s98, 0x2000
	s_addc_u32 s99, s99, 0
	global_load_lds_dwordx4 v246, s[98:99]
	s_mov_b32 m0, s101
	s_add_i32 s101, s2, 64
	s_lshl_b32 s101, s101, 8
	s_add_u32 s98, s76, s101
	s_addc_u32 s99, s77, 0
	global_load_lds_dwordx4 v247, s[98:99]
	s_add_i32 m0, m0, 0x2000
	s_add_u32 s98, s98, 0x2000
	s_addc_u32 s99, s99, 0
	global_load_lds_dwordx4 v247, s[98:99]
	s_lshl_b32 s101, s2, 8
	s_add_u32 s98, s74, s101
	s_addc_u32 s99, s75, 0
	s_and_b32 s101, s0, 0xc000
	s_add_i32 m0, s1, s101
	s_add_i32 s101, s101, s8
	global_load_lds_dwordx4 v246, s[98:99]
	s_add_i32 m0, m0, 0x2000
	s_add_u32 s98, s98, 0x2000
	s_addc_u32 s99, s99, 0
	global_load_lds_dwordx4 v246, s[98:99]
	s_mov_b32 m0, s101
	s_lshl_b32 s101, s2, 8
	s_add_u32 s98, s76, s101
	s_addc_u32 s99, s77, 0
	global_load_lds_dwordx4 v247, s[98:99]
	s_add_i32 m0, m0, 0x2000
	s_add_u32 s98, s98, 0x2000
	s_addc_u32 s99, s99, 0
	global_load_lds_dwordx4 v247, s[98:99]

.LBB0_950:
	s_cmp_eq_u32 s100, 0
	s_cbranch_scc1 .Lnd_943
	s_add_i32 s101, s2, 64
	s_lshl_b32 s101, s101, 8
	s_add_u32 s98, s74, s101
	s_addc_u32 s99, s75, 0
	s_add_i32 s101, s0, 0x4000
	s_and_b32 s101, s101, 0xc000
	s_add_i32 m0, s1, s101
	s_add_i32 s101, s101, s8
	global_load_lds_dwordx4 v246, s[98:99]
	s_add_i32 m0, m0, 0x2000
	s_add_u32 s98, s98, 0x2000
	s_addc_u32 s99, s99, 0
	global_load_lds_dwordx4 v246, s[98:99]
	s_mov_b32 m0, s101
	s_add_i32 s101, s2, 64
	s_lshl_b32 s101, s101, 8
	s_add_u32 s98, s76, s101
	s_addc_u32 s99, s77, 0
	global_load_lds_dwordx4 v247, s[98:99]
	s_add_i32 m0, m0, 0x2000
	s_add_u32 s98, s98, 0x2000
	s_addc_u32 s99, s99, 0
	global_load_lds_dwordx4 v247, s[98:99]
	s_lshl_b32 s101, s2, 8
	s_add_u32 s98, s74, s101
	s_addc_u32 s99, s75, 0
	s_and_b32 s101, s0, 0xc000
	s_add_i32 m0, s1, s101
	s_add_i32 s101, s101, s8
	global_load_lds_dwordx4 v246, s[98:99]
	s_add_i32 m0, m0, 0x2000
	s_add_u32 s98, s98, 0x2000
	s_addc_u32 s99, s99, 0
	global_load_lds_dwordx4 v246, s[98:99]
	s_mov_b32 m0, s101
	s_lshl_b32 s101, s2, 8
	s_add_u32 s98, s76, s101
	s_addc_u32 s99, s77, 0
	global_load_lds_dwordx4 v247, s[98:99]
	s_add_i32 m0, m0, 0x2000
	s_add_u32 s98, s98, 0x2000
	s_addc_u32 s99, s99, 0
	global_load_lds_dwordx4 v247, s[98:99]
	s_mov_b32 s100, 0
